# P9: sample-row combine spread over all 256 workgroups (2 rows per workgroup) instead of 8 rows on each of 64 workgroups
# speedup vs baseline: 1.0073x; 1.0057x over previous
; #define FRESH_IDS() const int tid = fresh_tid(), lane = tid & 63, wid = __builtin_amdgcn_readfirstlane(tid >> 6); (void)tid; (void)lane; (void)wid
; __device__ __forceinline__ void sample_combine(const float* gate, const float* part, int nsk, int srow, f32x4 (&v)[4], int lane) {
; #pragma unroll
;     for (int j = 0; j < 4; ++j) { const int c4 = lane + 64 * j; f32x4 a = (f32x4){0.f, 0.f, 0.f, 0.f};
;         for (int k = 0; k < nsk; ++k) a += *((const f32x4*)(part + ((size_t)k * 512 + srow) * DM) + c4);
;         v[j] = v[j] + *((const f32x4*)gate + c4) * a; }
; }
; __global__ void __launch_bounds__(512, 2) mega_fwd(Args a) {
;     ...
;     { FRESH_IDS();
;         for (int sr = bx * 8 + wid; sr < MS; sr += G * 8) { const int b16 = 8 + (sr >> 6); f32x4 v[4];
;             row_load_bf16(X1B + (size_t)(MP + sr) * DM, v, lane);
;             sample_combine(MOD + (size_t)b16 * 6144 + 5120, PART, 11, sr, v, lane);
; #pragma unroll
;             for (int j = 0; j < 4; ++j) *((f32x4*)(out + (size_t)(MP + sr) * DM) + lane + 64 * j) = v[j]; } }
.LBB0_1320:
	s_or_b64 exec, exec, s[0:1]
	s_waitcnt lgkmcnt(0)
	s_barrier
	v_readlane_b32 s3, v238, 46
	v_readfirstlane_b32 s0, v211
	s_ashr_i32 s0, s0, 6
	s_lshl_b32 s0, s0, 8
	s_lshr_b32 s3, s3, 3
	s_add_i32 s6, s0, s3
	s_cmpk_gt_i32 s6, 0x1ff
	s_cbranch_scc1 .LBB0_1323
	s_ashr_i32 s1, s0, 31
	s_ashr_i32 s2, s3, 31
	s_add_u32 s0, s0, s3
	v_and_b32_e32 v6, 63, v211
	s_addc_u32 s1, s1, s2
	s_lshl_b64 s[0:1], s[0:1], 12
	v_lshlrev_b32_e32 v2, 4, v6
	v_or_b32_e32 v0, s0, v2
	s_add_i32 s0, s6, 0x8000
	v_mov_b32_e32 v1, s1
	s_ashr_i32 s89, s88, 31
	s_ashr_i32 s1, s0, 31
	s_lshl_b64 s[2:3], s[88:89], 12
	s_lshl_b64 s[4:5], s[0:1], 12
	s_add_u32 s4, s28, s4
	v_mov_b32_e32 v3, 0
	s_addc_u32 s5, s29, s5
	v_or_b32_e32 v8, 64, v6
	v_or_b32_e32 v12, 0x80, v6
	v_or_b32_e32 v14, 0xc0, v6
	v_lshl_add_u64 v[2:3], s[4:5], 0, v[2:3]
	s_mov_b64 s[4:5], 0x800
	s_lshl_b64 s[0:1], s[0:1], 11
	v_lshl_add_u64 v[2:3], v[2:3], 0, s[4:5]
	v_lshl_or_b32 v4, v6, 3, s0
	v_mov_b32_e32 v5, s1
	s_lshl_b64 s[4:5], s[88:89], 11
	s_mov_b32 s7, 0x1aa00000
	s_mov_b32 s8, 0x1ac00000
	s_mov_b32 s9, 0x1ae00000
	s_mov_b32 s10, 0x1b000000
	s_mov_b32 s11, 0x1b200000
	s_mov_b32 s12, 0x1b400000
	s_mov_b32 s13, 0x1b600000
	s_mov_b32 s14, 0x1b800000
	s_mov_b32 s15, 0x1ba00000
	s_mov_b32 s16, 0x1bc00000
	s_mov_b32 s17, 0x1be00000
	v_lshlrev_b32_e32 v10, 4, v6
	v_lshlrev_b32_e32 v11, 4, v8
	v_lshlrev_b32_e32 v12, 4, v12
	v_lshlrev_b32_e32 v13, 4, v14
